# layer-0 RMSNorm (4 unrolled rows): all four x loads of each row issued together, partial-sum and lane-index temporaries renamed out of the load destination registers
# speedup vs baseline: 1.0211x; 1.0088x over previous
.LBB0_1076:
	s_or_b64 exec, exec, s[0:1]
	v_lshlrev_b32_e32 v1, 2, v1
	v_and_b32_e32 v47, 0xfc, v1
	v_lshlrev_b32_e32 v20, 2, v47
	v_mov_b32_e32 v21, v0
	v_lshl_add_u64 v[2:3], v[2:3], 0, v[20:21]
	global_load_dwordx4 v[14:17], v[2:3], off
	global_load_dwordx4 v[10:13], v[2:3], off offset:1024
	global_load_dwordx4 v[6:9], v[2:3], off offset:2048
	s_nop 0
	global_load_dwordx4 v[2:5], v[2:3], off offset:3072
	v_and_b32_e32 v1, 64, v195
	v_add_u32_e32 v251, 64, v1
	v_xor_b32_e32 v1, 32, v195
	v_cmp_lt_i32_e32 vcc, v1, v251
	v_xor_b32_e32 v252, 16, v195
	s_mov_b32 s0, 0x800000
	v_cndmask_b32_e32 v1, v195, v1, vcc
	v_cmp_lt_i32_e32 vcc, v252, v251
	v_lshlrev_b32_e32 v1, 2, v1
	v_readlane_b32 s36, v248, 6
	v_cndmask_b32_e32 v252, v195, v252, vcc
	v_lshlrev_b32_e32 v42, 2, v252
	v_xor_b32_e32 v252, 8, v195
	v_cmp_lt_i32_e32 vcc, v252, v251
	v_readlane_b32 s48, v248, 18
	v_readlane_b32 s49, v248, 19
	v_cndmask_b32_e32 v252, v195, v252, vcc
	v_lshlrev_b32_e32 v43, 2, v252
	v_xor_b32_e32 v252, 4, v195
	v_cmp_lt_i32_e32 vcc, v252, v251
	v_or_b32_e32 v33, 0x300, v47
	v_or_b32_e32 v37, 0x100, v47
	v_cndmask_b32_e32 v252, v195, v252, vcc
	v_lshlrev_b32_e32 v44, 2, v252
	v_xor_b32_e32 v252, 2, v195
	v_cmp_lt_i32_e32 vcc, v252, v251
	v_or_b32_e32 v36, 0x200, v47
	v_readlane_b32 s37, v248, 7
	v_cndmask_b32_e32 v252, v195, v252, vcc
	v_lshlrev_b32_e32 v45, 2, v252
	v_xor_b32_e32 v252, 1, v195
	v_cmp_lt_i32_e32 vcc, v252, v251
	v_readlane_b32 s38, v248, 8
	v_readlane_b32 s39, v248, 9
	v_cndmask_b32_e32 v251, v195, v252, vcc
	v_lshlrev_b32_e32 v46, 2, v251
	v_readlane_b32 s40, v248, 10
	v_readlane_b32 s41, v248, 11
	v_readlane_b32 s42, v248, 12
	v_readlane_b32 s43, v248, 13
	v_readlane_b32 s44, v248, 14
	v_readlane_b32 s45, v248, 15
	v_readlane_b32 s46, v248, 16
	s_nop 0
	v_readlane_b32 s47, v248, 17
	s_nop 0
	v_readlane_b32 s50, v248, 20
	s_nop 0
	v_readlane_b32 s51, v248, 21
	s_nop 0
	s_waitcnt vmcnt(3)
	s_waitcnt vmcnt(2)
	v_mul_f32_e32 v249, v15, v15
	v_mul_f32_e32 v250, v11, v11
	s_nop 0
	v_fma_f32 v251, v14, v14, v249
	v_fma_f32 v252, v10, v10, v250
	v_fma_f32 v251, v16, v16, v251
	v_fma_f32 v252, v12, v12, v252
	v_fma_f32 v26, v17, v17, v251
	v_fma_f32 v27, v13, v13, v252
	v_add_f32_e32 v26, v26, v27
	global_load_dwordx4 v[38:41], v20, s[48:49]
	s_waitcnt vmcnt(2)
	s_waitcnt vmcnt(1)
	v_mul_f32_e32 v30, v7, v7
	v_mul_f32_e32 v31, v3, v3
	s_nop 0
	v_fma_f32 v28, v6, v6, v30
	v_fma_f32 v29, v2, v2, v31
	v_fma_f32 v28, v8, v8, v28
	v_fma_f32 v29, v4, v4, v29
	v_fma_f32 v28, v9, v9, v28
	v_fma_f32 v29, v5, v5, v29
	s_nop 0
	v_add_f32_e32 v26, v26, v28
	v_add_f32_e32 v26, v26, v29
	ds_bpermute_b32 v27, v1, v26
	s_nop 2
	s_waitcnt lgkmcnt(0)
	v_add_f32_e32 v26, v26, v27
	ds_bpermute_b32 v27, v42, v26
	s_nop 2
	s_waitcnt lgkmcnt(0)
	v_add_f32_e32 v26, v26, v27
	ds_bpermute_b32 v27, v43, v26
	s_nop 2
	s_waitcnt lgkmcnt(0)
	v_add_f32_e32 v26, v26, v27
	ds_bpermute_b32 v27, v44, v26
	s_nop 2
	s_waitcnt lgkmcnt(0)
	v_add_f32_e32 v26, v26, v27
	ds_bpermute_b32 v27, v45, v26
	s_nop 2
	s_waitcnt lgkmcnt(0)
	v_add_f32_e32 v26, v26, v27
	ds_bpermute_b32 v27, v46, v26
	s_waitcnt lgkmcnt(0)
	v_add_f32_e32 v26, v26, v27
	v_fmamk_f32 v26, v26, 0x3a800000, v188
	v_cmp_gt_f32_e32 vcc, s0, v26
	v_readlane_b32 s0, v245, 5
	v_readlane_b32 s1, v245, 6
	v_mul_f32_e32 v27, 0x4b800000, v26
	v_cndmask_b32_e32 v26, v26, v27, vcc
	v_lshl_add_u64 v[22:23], v[22:23], 2, s[0:1]
	s_mov_b64 s[0:1], 0x1000
	v_lshl_add_u64 v[34:35], v[22:23], 0, s[0:1]
	v_lshl_add_u64 v[30:31], v[22:23], 0, v[20:21]
	v_lshl_add_u64 v[22:23], v[34:35], 0, v[20:21]
	global_load_dwordx4 v[48:51], v[30:31], off
	global_load_dwordx4 v[52:55], v[22:23], off
	v_rsq_f32_e32 v26, v26
	v_readlane_b32 s0, v247, 56
	v_readlane_b32 s1, v247, 57
	v_mul_f32_e32 v27, 0x45800000, v26
	v_cndmask_b32_e32 v32, v26, v27, vcc
	v_pk_mul_f32 v[14:15], v[14:15], v[32:33] op_sel_hi:[1,0]
	v_lshlrev_b64 v[26:27], 11, v[24:25]
	s_waitcnt vmcnt(2)
	v_pk_mul_f32 v[14:15], v[38:39], v[14:15]
	v_lshl_add_u64 v[26:27], s[0:1], 0, v[26:27]
	v_pk_mul_f32 v[10:11], v[10:11], v[32:33] op_sel_hi:[1,0]
	v_pk_mul_f32 v[12:13], v[12:13], v[32:33] op_sel_hi:[1,0]
	v_pk_mul_f32 v[6:7], v[6:7], v[32:33] op_sel_hi:[1,0]
	v_pk_mul_f32 v[8:9], v[8:9], v[32:33] op_sel_hi:[1,0]
	v_pk_mul_f32 v[2:3], v[2:3], v[32:33] op_sel_hi:[1,0]
	v_pk_mul_f32 v[4:5], v[4:5], v[32:33] op_sel_hi:[1,0]
	s_waitcnt vmcnt(0)
	v_pk_add_f32 v[22:23], v[52:53], 1.0 op_sel_hi:[1,0]
	s_nop 0
	v_pk_fma_f32 v[14:15], v[22:23], v[14:15], v[48:49]
	v_lshlrev_b32_e32 v22, 1, v47
	v_cvt_pk_bf16_f32 v28, v14, v15
	v_pk_mul_f32 v[14:15], v[16:17], v[32:33] op_sel_hi:[1,0]
	v_pk_add_f32 v[16:17], v[54:55], 1.0 op_sel_hi:[1,0]
	v_pk_mul_f32 v[14:15], v[40:41], v[14:15]
	v_mov_b32_e32 v23, v0
	v_pk_fma_f32 v[14:15], v[16:17], v[14:15], v[50:51]
	s_nop 0
	v_cvt_pk_bf16_f32 v29, v14, v15
	v_lshl_add_u64 v[14:15], v[26:27], 0, v[22:23]
	v_lshlrev_b32_e32 v26, 2, v37
	v_mov_b32_e32 v27, v0
	global_store_dwordx2 v[14:15], v[28:29], off
	v_lshl_add_u64 v[16:17], v[34:35], 0, v[26:27]
	global_load_dwordx4 v[38:41], v20, s[48:49] offset:1024
	global_load_dwordx4 v[48:51], v[30:31], off offset:1024
	global_load_dwordx4 v[52:55], v[16:17], off
	v_lshlrev_b32_e32 v28, 2, v36
	v_mov_b32_e32 v29, v0
	s_waitcnt vmcnt(2)
	v_pk_mul_f32 v[10:11], v[38:39], v[10:11]
	v_pk_mul_f32 v[12:13], v[40:41], v[12:13]
	s_waitcnt vmcnt(0)
	v_pk_add_f32 v[16:17], v[52:53], 1.0 op_sel_hi:[1,0]
	s_nop 0
	v_pk_fma_f32 v[10:11], v[16:17], v[10:11], v[48:49]
	v_pk_add_f32 v[16:17], v[54:55], 1.0 op_sel_hi:[1,0]
	v_cvt_pk_bf16_f32 v10, v10, v11
	v_pk_fma_f32 v[12:13], v[16:17], v[12:13], v[50:51]
	v_lshl_add_u64 v[16:17], v[34:35], 0, v[28:29]
	v_cvt_pk_bf16_f32 v11, v12, v13
	global_store_dwordx2 v[14:15], v[10:11], off offset:512
	global_load_dwordx4 v[10:13], v20, s[48:49] offset:2048
	s_nop 0
	global_load_dwordx4 v[38:41], v[30:31], off offset:2048
	global_load_dwordx4 v[48:51], v[16:17], off
	s_waitcnt vmcnt(2)
	v_pk_mul_f32 v[6:7], v[10:11], v[6:7]
	v_pk_mul_f32 v[8:9], v[12:13], v[8:9]
	s_waitcnt vmcnt(0)
	v_pk_add_f32 v[10:11], v[48:49], 1.0 op_sel_hi:[1,0]
	s_nop 0
	v_pk_fma_f32 v[6:7], v[10:11], v[6:7], v[38:39]
	v_pk_add_f32 v[10:11], v[50:51], 1.0 op_sel_hi:[1,0]
	v_cvt_pk_bf16_f32 v6, v6, v7
	v_pk_fma_f32 v[8:9], v[10:11], v[8:9], v[40:41]
	v_or_b32_e32 v38, 1, v24
	v_cvt_pk_bf16_f32 v7, v8, v9
	global_store_dwordx2 v[14:15], v[6:7], off offset:1024
	global_load_dwordx4 v[6:9], v20, s[48:49] offset:3072
	s_nop 0
	global_load_dwordx4 v[10:13], v[30:31], off offset:3072
	v_lshlrev_b32_e32 v30, 2, v33
	v_mov_b32_e32 v31, v0
	v_lshl_add_u64 v[16:17], v[34:35], 0, v[30:31]
	global_load_dwordx4 v[34:37], v[16:17], off
	v_cmp_lt_i32_e32 vcc, s4, v38
	s_waitcnt vmcnt(2)
	v_pk_mul_f32 v[2:3], v[6:7], v[2:3]
	v_pk_mul_f32 v[4:5], v[8:9], v[4:5]
	s_waitcnt vmcnt(0)
	v_pk_add_f32 v[6:7], v[34:35], 1.0 op_sel_hi:[1,0]
	s_nop 0
	v_pk_fma_f32 v[2:3], v[2:3], v[6:7], v[10:11]
	v_pk_add_f32 v[6:7], v[36:37], 1.0 op_sel_hi:[1,0]
	v_cvt_pk_bf16_f32 v2, v2, v3
	v_pk_fma_f32 v[4:5], v[4:5], v[6:7], v[12:13]
	s_nop 0
	v_cvt_pk_bf16_f32 v3, v4, v5
	global_store_dwordx2 v[14:15], v[2:3], off offset:1536
	s_and_saveexec_b64 s[0:1], vcc
	s_xor_b64 s[0:1], exec, s[0:1]
	s_cbranch_execz .LBB0_1078
	v_add_u32_e32 v2, 0xffffe001, v24
	v_mov_b32_e32 v3, v0
	v_readlane_b32 s36, v248, 6
	v_lshlrev_b64 v[2:3], 12, v[2:3]
	v_readlane_b32 s38, v248, 8
	v_readlane_b32 s39, v248, 9
	v_mov_b32_e32 v39, v0
	v_readlane_b32 s37, v248, 7
	v_lshl_add_u64 v[2:3], s[38:39], 0, v[2:3]
	v_readlane_b32 s40, v248, 10
	v_readlane_b32 s41, v248, 11
	v_readlane_b32 s42, v248, 12
	v_readlane_b32 s43, v248, 13
	v_readlane_b32 s44, v248, 14
	v_readlane_b32 s45, v248, 15
	v_readlane_b32 s46, v248, 16
	v_readlane_b32 s47, v248, 17
	v_readlane_b32 s48, v248, 18
	v_readlane_b32 s49, v248, 19
	v_readlane_b32 s50, v248, 20
	v_readlane_b32 s51, v248, 21

.LBB0_1080:
	s_or_b64 exec, exec, s[0:1]
	v_readlane_b32 s36, v248, 6
	v_readlane_b32 s48, v248, 18
	v_readlane_b32 s49, v248, 19
	s_mov_b32 s0, 0x800000
	v_lshlrev_b64 v[38:39], 11, v[38:39]
	v_lshl_add_u64 v[32:33], s[48:49], 0, v[20:21]
	v_mov_b32_e32 v21, v0
	v_lshl_add_u64 v[2:3], v[2:3], 0, v[20:21]
	global_load_dwordx4 v[14:17], v[2:3], off
	global_load_dwordx4 v[10:13], v[2:3], off offset:1024
	global_load_dwordx4 v[6:9], v[2:3], off offset:2048
	s_nop 0
	global_load_dwordx4 v[2:5], v[2:3], off offset:3072
	v_mov_b32_e32 v27, v0
	v_mov_b32_e32 v29, v0
	v_mov_b32_e32 v31, v0
	v_readlane_b32 s43, v248, 13
	s_movk_i32 s43, 0x1fff
	v_readlane_b32 s37, v248, 7
	v_readlane_b32 s38, v248, 8
	v_readlane_b32 s39, v248, 9
	v_readlane_b32 s40, v248, 10
	v_readlane_b32 s41, v248, 11
	v_readlane_b32 s42, v248, 12
	v_readlane_b32 s44, v248, 14
	v_readlane_b32 s45, v248, 15
	v_readlane_b32 s46, v248, 16
	s_nop 0
	v_readlane_b32 s47, v248, 17
	s_nop 0
	v_readlane_b32 s50, v248, 20
	s_nop 0
	v_readlane_b32 s51, v248, 21
	s_nop 0
	s_waitcnt vmcnt(3)
	s_waitcnt vmcnt(2)
	v_mul_f32_e32 v249, v15, v15
	v_mul_f32_e32 v250, v11, v11
	s_nop 0
	v_fma_f32 v251, v14, v14, v249
	v_fma_f32 v252, v10, v10, v250
	v_fma_f32 v251, v16, v16, v251
	v_fma_f32 v252, v12, v12, v252
	v_fma_f32 v34, v17, v17, v251
	v_fma_f32 v35, v13, v13, v252
	v_add_f32_e32 v23, v34, v35
	s_waitcnt vmcnt(1)
	s_waitcnt vmcnt(0)
	v_mul_f32_e32 v48, v7, v7
	v_mul_f32_e32 v49, v3, v3
	s_nop 0
	v_fma_f32 v40, v6, v6, v48
	v_fma_f32 v41, v2, v2, v49
	v_fma_f32 v40, v8, v8, v40
	v_fma_f32 v41, v4, v4, v41
	v_fma_f32 v40, v9, v9, v40
	v_fma_f32 v41, v5, v5, v41
	global_load_dwordx4 v[48:51], v[32:33], off
	v_add_f32_e32 v23, v23, v40
	v_add_f32_e32 v23, v23, v41
	ds_bpermute_b32 v25, v1, v23
	s_nop 2
	s_waitcnt lgkmcnt(0)
	v_add_f32_e32 v23, v23, v25
	ds_bpermute_b32 v25, v42, v23
	s_nop 2
	s_waitcnt lgkmcnt(0)
	v_add_f32_e32 v23, v23, v25
	ds_bpermute_b32 v25, v43, v23
	s_nop 2
	s_waitcnt lgkmcnt(0)
	v_add_f32_e32 v23, v23, v25
	ds_bpermute_b32 v25, v44, v23
	s_nop 2
	s_waitcnt lgkmcnt(0)
	v_add_f32_e32 v23, v23, v25
	ds_bpermute_b32 v25, v45, v23
	s_nop 2
	s_waitcnt lgkmcnt(0)
	v_add_f32_e32 v23, v23, v25
	ds_bpermute_b32 v25, v46, v23
	s_waitcnt lgkmcnt(0)
	v_add_f32_e32 v23, v23, v25
	v_fmamk_f32 v23, v23, 0x3a800000, v188
	v_cmp_gt_f32_e32 vcc, s0, v23
	v_readlane_b32 s0, v245, 5
	v_readlane_b32 s1, v245, 6
	v_mul_f32_e32 v25, 0x4b800000, v23
	v_cndmask_b32_e32 v23, v23, v25, vcc
	v_lshl_add_u64 v[52:53], v[36:37], 2, s[0:1]
	s_mov_b64 s[0:1], 0x1000
	v_lshl_add_u64 v[36:37], v[52:53], 0, s[0:1]
	v_readlane_b32 s0, v247, 56
	v_readlane_b32 s1, v247, 57
	v_lshl_add_u64 v[56:57], v[36:37], 0, v[20:21]
	global_load_dwordx4 v[56:59], v[56:57], off
	v_lshl_add_u64 v[40:41], s[0:1], 0, v[38:39]
	v_lshl_add_u64 v[38:39], v[52:53], 0, v[20:21]
	global_load_dwordx4 v[52:55], v[38:39], off
	v_rsq_f32_e32 v23, v23
	s_nop 0
	v_mul_f32_e32 v25, 0x45800000, v23
	v_cndmask_b32_e32 v34, v23, v25, vcc
	v_pk_mul_f32 v[14:15], v[14:15], v[34:35] op_sel_hi:[1,0]
	v_mov_b32_e32 v23, v0
	v_pk_mul_f32 v[10:11], v[10:11], v[34:35] op_sel_hi:[1,0]
	v_pk_mul_f32 v[12:13], v[12:13], v[34:35] op_sel_hi:[1,0]
	v_pk_mul_f32 v[6:7], v[6:7], v[34:35] op_sel_hi:[1,0]
	v_pk_mul_f32 v[8:9], v[8:9], v[34:35] op_sel_hi:[1,0]
	v_pk_mul_f32 v[2:3], v[2:3], v[34:35] op_sel_hi:[1,0]
	v_pk_mul_f32 v[4:5], v[4:5], v[34:35] op_sel_hi:[1,0]
	s_waitcnt vmcnt(2)
	v_pk_mul_f32 v[14:15], v[48:49], v[14:15]
	s_waitcnt vmcnt(1)
	v_pk_add_f32 v[48:49], v[56:57], 1.0 op_sel_hi:[1,0]
	s_waitcnt vmcnt(0)
	v_pk_fma_f32 v[14:15], v[48:49], v[14:15], v[52:53]
	s_nop 0
	v_cvt_pk_bf16_f32 v48, v14, v15
	v_pk_mul_f32 v[14:15], v[16:17], v[34:35] op_sel_hi:[1,0]
	v_pk_add_f32 v[16:17], v[58:59], 1.0 op_sel_hi:[1,0]
	v_pk_mul_f32 v[14:15], v[50:51], v[14:15]
	s_nop 0
	v_pk_fma_f32 v[14:15], v[16:17], v[14:15], v[54:55]
	v_lshl_add_u64 v[16:17], v[36:37], 0, v[26:27]
	v_cvt_pk_bf16_f32 v49, v14, v15
	v_lshl_add_u64 v[14:15], v[40:41], 0, v[22:23]
	global_store_dwordx2 v[14:15], v[48:49], off
	global_load_dwordx4 v[48:51], v[32:33], off offset:1024
	s_nop 0
	global_load_dwordx4 v[52:55], v[38:39], off offset:1024
	global_load_dwordx4 v[56:59], v[16:17], off
	s_waitcnt vmcnt(2)
	v_pk_mul_f32 v[10:11], v[48:49], v[10:11]
	v_pk_mul_f32 v[12:13], v[50:51], v[12:13]
	s_waitcnt vmcnt(0)
	v_pk_add_f32 v[16:17], v[56:57], 1.0 op_sel_hi:[1,0]
	s_nop 0
	v_pk_fma_f32 v[10:11], v[16:17], v[10:11], v[52:53]
	v_pk_add_f32 v[16:17], v[58:59], 1.0 op_sel_hi:[1,0]
	v_cvt_pk_bf16_f32 v10, v10, v11
	v_pk_fma_f32 v[12:13], v[16:17], v[12:13], v[54:55]
	v_lshl_add_u64 v[16:17], v[36:37], 0, v[28:29]
	v_cvt_pk_bf16_f32 v11, v12, v13
	global_store_dwordx2 v[14:15], v[10:11], off offset:512
	global_load_dwordx4 v[10:13], v[32:33], off offset:2048
	s_nop 0
	global_load_dwordx4 v[48:51], v[38:39], off offset:2048
	global_load_dwordx4 v[52:55], v[16:17], off
	v_lshl_add_u64 v[16:17], v[36:37], 0, v[30:31]
	s_waitcnt vmcnt(2)
	v_pk_mul_f32 v[6:7], v[10:11], v[6:7]
	v_pk_mul_f32 v[8:9], v[12:13], v[8:9]
	s_waitcnt vmcnt(0)
	v_pk_add_f32 v[10:11], v[52:53], 1.0 op_sel_hi:[1,0]
	s_nop 0
	v_pk_fma_f32 v[6:7], v[10:11], v[6:7], v[48:49]
	v_pk_add_f32 v[10:11], v[54:55], 1.0 op_sel_hi:[1,0]
	v_cvt_pk_bf16_f32 v6, v6, v7
	v_pk_fma_f32 v[8:9], v[10:11], v[8:9], v[50:51]
	s_nop 0
	v_cvt_pk_bf16_f32 v7, v8, v9
	global_store_dwordx2 v[14:15], v[6:7], off offset:1024
	global_load_dwordx4 v[6:9], v[32:33], off offset:3072
	s_nop 0
	global_load_dwordx4 v[10:13], v[38:39], off offset:3072
	s_waitcnt vmcnt(1)
	v_pk_mul_f32 v[2:3], v[6:7], v[2:3]
	global_load_dwordx4 v[36:39], v[16:17], off
	v_pk_mul_f32 v[4:5], v[8:9], v[4:5]
	s_waitcnt vmcnt(0)
	v_pk_add_f32 v[6:7], v[36:37], 1.0 op_sel_hi:[1,0]
	s_nop 0
	v_pk_fma_f32 v[2:3], v[2:3], v[6:7], v[10:11]
	v_pk_add_f32 v[6:7], v[38:39], 1.0 op_sel_hi:[1,0]
	v_or_b32_e32 v38, 2, v24
	v_pk_fma_f32 v[4:5], v[4:5], v[6:7], v[12:13]
	v_cvt_pk_bf16_f32 v2, v2, v3
	v_cvt_pk_bf16_f32 v3, v4, v5
	v_cmp_lt_i32_e32 vcc, s43, v38
	global_store_dwordx2 v[14:15], v[2:3], off offset:1536
	s_and_saveexec_b64 s[0:1], vcc
	s_xor_b64 s[0:1], exec, s[0:1]
	s_cbranch_execz .LBB0_1082
	v_add_u32_e32 v2, 0xffffe002, v24
	v_mov_b32_e32 v3, v0
	v_readlane_b32 s36, v248, 6
	v_lshlrev_b64 v[2:3], 12, v[2:3]
	v_readlane_b32 s38, v248, 8
	v_readlane_b32 s39, v248, 9
	v_readlane_b32 s43, v248, 13
	s_movk_i32 s43, 0x1fff
	v_lshl_add_u64 v[2:3], s[38:39], 0, v[2:3]
	v_mov_b32_e32 v39, v0
	v_readlane_b32 s37, v248, 7
	v_readlane_b32 s40, v248, 10
	v_readlane_b32 s41, v248, 11
	v_readlane_b32 s42, v248, 12
	v_readlane_b32 s44, v248, 14
	v_readlane_b32 s45, v248, 15
	v_readlane_b32 s46, v248, 16
	v_readlane_b32 s47, v248, 17
	v_readlane_b32 s48, v248, 18
	v_readlane_b32 s49, v248, 19
	v_readlane_b32 s50, v248, 20
	v_readlane_b32 s51, v248, 21

.LBB0_1084:
	s_or_b64 exec, exec, s[0:1]
	v_mov_b32_e32 v21, v0
	v_lshl_add_u64 v[2:3], v[2:3], 0, v[20:21]
	global_load_dwordx4 v[14:17], v[2:3], off
	global_load_dwordx4 v[10:13], v[2:3], off offset:1024
	global_load_dwordx4 v[6:9], v[2:3], off offset:2048
	s_nop 0
	global_load_dwordx4 v[2:5], v[2:3], off offset:3072
	s_mov_b32 s0, 0x800000
	v_lshlrev_b64 v[38:39], 11, v[38:39]
	v_mov_b32_e32 v27, v0
	v_mov_b32_e32 v29, v0
	v_mov_b32_e32 v31, v0
	s_waitcnt vmcnt(3)
	s_waitcnt vmcnt(2)
	v_mul_f32_e32 v249, v15, v15
	v_mul_f32_e32 v250, v11, v11
	s_nop 0
	v_fma_f32 v251, v14, v14, v249
	v_fma_f32 v252, v10, v10, v250
	v_fma_f32 v251, v16, v16, v251
	v_fma_f32 v252, v12, v12, v252
	v_fma_f32 v34, v17, v17, v251
	v_fma_f32 v35, v13, v13, v252
	v_add_f32_e32 v23, v34, v35
	s_waitcnt vmcnt(1)
	s_waitcnt vmcnt(0)
	v_mul_f32_e32 v48, v7, v7
	v_mul_f32_e32 v49, v3, v3
	s_nop 0
	v_fma_f32 v40, v6, v6, v48
	v_fma_f32 v41, v2, v2, v49
	v_fma_f32 v40, v8, v8, v40
	v_fma_f32 v41, v4, v4, v41
	v_fma_f32 v40, v9, v9, v40
	v_fma_f32 v41, v5, v5, v41
	global_load_dwordx4 v[48:51], v[32:33], off
	v_add_f32_e32 v23, v23, v40
	v_add_f32_e32 v23, v23, v41
	ds_bpermute_b32 v25, v1, v23
	s_nop 2
	s_waitcnt lgkmcnt(0)
	v_add_f32_e32 v23, v23, v25
	ds_bpermute_b32 v25, v42, v23
	s_nop 2
	s_waitcnt lgkmcnt(0)
	v_add_f32_e32 v23, v23, v25
	ds_bpermute_b32 v25, v43, v23
	s_nop 2
	s_waitcnt lgkmcnt(0)
	v_add_f32_e32 v23, v23, v25
	ds_bpermute_b32 v25, v44, v23
	s_nop 2
	s_waitcnt lgkmcnt(0)
	v_add_f32_e32 v23, v23, v25
	ds_bpermute_b32 v25, v45, v23
	s_nop 2
	s_waitcnt lgkmcnt(0)
	v_add_f32_e32 v23, v23, v25
	ds_bpermute_b32 v25, v46, v23
	s_waitcnt lgkmcnt(0)
	v_add_f32_e32 v23, v23, v25
	v_fmamk_f32 v23, v23, 0x3a800000, v188
	v_cmp_gt_f32_e32 vcc, s0, v23
	v_readlane_b32 s0, v245, 5
	v_readlane_b32 s1, v245, 6
	v_mul_f32_e32 v25, 0x4b800000, v23
	v_cndmask_b32_e32 v23, v23, v25, vcc
	v_lshl_add_u64 v[52:53], v[36:37], 2, s[0:1]
	s_mov_b64 s[0:1], 0x1000
	v_lshl_add_u64 v[36:37], v[52:53], 0, s[0:1]
	v_readlane_b32 s0, v247, 56
	v_readlane_b32 s1, v247, 57
	v_lshl_add_u64 v[56:57], v[36:37], 0, v[20:21]
	global_load_dwordx4 v[56:59], v[56:57], off
	v_lshl_add_u64 v[40:41], s[0:1], 0, v[38:39]
	v_lshl_add_u64 v[38:39], v[52:53], 0, v[20:21]
	global_load_dwordx4 v[52:55], v[38:39], off
	v_rsq_f32_e32 v23, v23
	s_nop 0
	v_mul_f32_e32 v25, 0x45800000, v23
	v_cndmask_b32_e32 v34, v23, v25, vcc
	v_pk_mul_f32 v[14:15], v[14:15], v[34:35] op_sel_hi:[1,0]
	v_mov_b32_e32 v23, v0
	v_pk_mul_f32 v[10:11], v[10:11], v[34:35] op_sel_hi:[1,0]
	v_pk_mul_f32 v[12:13], v[12:13], v[34:35] op_sel_hi:[1,0]
	v_pk_mul_f32 v[6:7], v[6:7], v[34:35] op_sel_hi:[1,0]
	v_pk_mul_f32 v[8:9], v[8:9], v[34:35] op_sel_hi:[1,0]
	v_pk_mul_f32 v[2:3], v[2:3], v[34:35] op_sel_hi:[1,0]
	v_pk_mul_f32 v[4:5], v[4:5], v[34:35] op_sel_hi:[1,0]
	s_waitcnt vmcnt(2)
	v_pk_mul_f32 v[14:15], v[48:49], v[14:15]
	s_waitcnt vmcnt(1)
	v_pk_add_f32 v[48:49], v[56:57], 1.0 op_sel_hi:[1,0]
	s_waitcnt vmcnt(0)
	v_pk_fma_f32 v[14:15], v[48:49], v[14:15], v[52:53]
	s_nop 0
	v_cvt_pk_bf16_f32 v48, v14, v15
	v_pk_mul_f32 v[14:15], v[16:17], v[34:35] op_sel_hi:[1,0]
	v_pk_add_f32 v[16:17], v[58:59], 1.0 op_sel_hi:[1,0]
	v_pk_mul_f32 v[14:15], v[50:51], v[14:15]
	v_or_b32_e32 v34, 3, v24
	v_pk_fma_f32 v[14:15], v[16:17], v[14:15], v[54:55]
	v_lshl_add_u64 v[16:17], v[36:37], 0, v[26:27]
	v_cvt_pk_bf16_f32 v49, v14, v15
	v_lshl_add_u64 v[14:15], v[40:41], 0, v[22:23]
	global_store_dwordx2 v[14:15], v[48:49], off
	global_load_dwordx4 v[48:51], v[32:33], off offset:1024
	s_nop 0
	global_load_dwordx4 v[52:55], v[38:39], off offset:1024
	global_load_dwordx4 v[56:59], v[16:17], off
	v_cmp_lt_i32_e32 vcc, s43, v34
	s_waitcnt vmcnt(2)
	v_pk_mul_f32 v[10:11], v[48:49], v[10:11]
	v_pk_mul_f32 v[12:13], v[50:51], v[12:13]
	s_waitcnt vmcnt(0)
	v_pk_add_f32 v[16:17], v[56:57], 1.0 op_sel_hi:[1,0]
	s_nop 0
	v_pk_fma_f32 v[10:11], v[16:17], v[10:11], v[52:53]
	v_pk_add_f32 v[16:17], v[58:59], 1.0 op_sel_hi:[1,0]
	v_cvt_pk_bf16_f32 v10, v10, v11
	v_pk_fma_f32 v[12:13], v[16:17], v[12:13], v[54:55]
	v_lshl_add_u64 v[16:17], v[36:37], 0, v[28:29]
	v_cvt_pk_bf16_f32 v11, v12, v13
	global_store_dwordx2 v[14:15], v[10:11], off offset:512
	global_load_dwordx4 v[10:13], v[32:33], off offset:2048
	s_nop 0
	global_load_dwordx4 v[48:51], v[38:39], off offset:2048
	global_load_dwordx4 v[52:55], v[16:17], off
	v_lshl_add_u64 v[16:17], v[36:37], 0, v[30:31]
	s_waitcnt vmcnt(2)
	v_pk_mul_f32 v[6:7], v[10:11], v[6:7]
	v_pk_mul_f32 v[8:9], v[12:13], v[8:9]
	s_waitcnt vmcnt(0)
	v_pk_add_f32 v[10:11], v[52:53], 1.0 op_sel_hi:[1,0]
	s_nop 0
	v_pk_fma_f32 v[6:7], v[10:11], v[6:7], v[48:49]
	v_pk_add_f32 v[10:11], v[54:55], 1.0 op_sel_hi:[1,0]
	v_cvt_pk_bf16_f32 v6, v6, v7
	v_pk_fma_f32 v[8:9], v[10:11], v[8:9], v[50:51]
	s_nop 0
	v_cvt_pk_bf16_f32 v7, v8, v9
	global_store_dwordx2 v[14:15], v[6:7], off offset:1024
	global_load_dwordx4 v[6:9], v[32:33], off offset:3072
	s_nop 0
	global_load_dwordx4 v[10:13], v[38:39], off offset:3072
	s_waitcnt vmcnt(1)
	v_pk_mul_f32 v[2:3], v[6:7], v[2:3]
	global_load_dwordx4 v[36:39], v[16:17], off
	v_pk_mul_f32 v[4:5], v[8:9], v[4:5]
	s_waitcnt vmcnt(0)
	v_pk_add_f32 v[6:7], v[36:37], 1.0 op_sel_hi:[1,0]
	s_nop 0
	v_pk_fma_f32 v[2:3], v[2:3], v[6:7], v[10:11]
	v_pk_add_f32 v[6:7], v[38:39], 1.0 op_sel_hi:[1,0]
	v_cvt_pk_bf16_f32 v2, v2, v3
	v_pk_fma_f32 v[4:5], v[4:5], v[6:7], v[12:13]
	s_nop 0
	v_cvt_pk_bf16_f32 v3, v4, v5
	global_store_dwordx2 v[14:15], v[2:3], off offset:1536
	s_and_saveexec_b64 s[0:1], vcc
	s_xor_b64 s[0:1], exec, s[0:1]
	s_cbranch_execz .LBB0_1086
	v_add_u32_e32 v2, 0xffffe003, v24
	v_mov_b32_e32 v3, v0
	v_readlane_b32 s36, v248, 6
	v_lshlrev_b64 v[2:3], 12, v[2:3]
	v_readlane_b32 s38, v248, 8
	v_readlane_b32 s39, v248, 9
	v_readlane_b32 s43, v248, 13
	s_movk_i32 s43, 0x1fff
	v_lshl_add_u64 v[2:3], s[38:39], 0, v[2:3]
	v_mov_b32_e32 v35, v0
	v_readlane_b32 s37, v248, 7
	v_readlane_b32 s40, v248, 10
	v_readlane_b32 s41, v248, 11
	v_readlane_b32 s42, v248, 12
	v_readlane_b32 s44, v248, 14
	v_readlane_b32 s45, v248, 15
	v_readlane_b32 s46, v248, 16
	v_readlane_b32 s47, v248, 17
	v_readlane_b32 s48, v248, 18
	v_readlane_b32 s49, v248, 19
	v_readlane_b32 s50, v248, 20
	v_readlane_b32 s51, v248, 21

.LBB0_1088:
	s_or_b64 exec, exec, s[0:1]
	v_mov_b32_e32 v21, v0
	v_lshl_add_u64 v[2:3], v[2:3], 0, v[20:21]
	global_load_dwordx4 v[14:17], v[2:3], off
	global_load_dwordx4 v[10:13], v[2:3], off offset:1024
	global_load_dwordx4 v[6:9], v[2:3], off offset:2048
	s_nop 0
	global_load_dwordx4 v[2:5], v[2:3], off offset:3072
	s_mov_b32 s0, 0x800000
	v_lshlrev_b64 v[34:35], 11, v[34:35]
	v_mov_b32_e32 v27, v0
	v_mov_b32_e32 v29, v0
	v_mov_b32_e32 v31, v0
	s_waitcnt vmcnt(3)
	s_waitcnt vmcnt(2)
	v_mul_f32_e32 v249, v15, v15
	v_mul_f32_e32 v250, v11, v11
	s_nop 0
	v_fma_f32 v251, v14, v14, v249
	v_fma_f32 v252, v10, v10, v250
	v_fma_f32 v251, v16, v16, v251
	v_fma_f32 v252, v12, v12, v252
	v_fma_f32 v24, v17, v17, v251
	v_fma_f32 v25, v13, v13, v252
	v_add_f32_e32 v23, v24, v25
	s_waitcnt vmcnt(1)
	s_waitcnt vmcnt(0)
	v_mul_f32_e32 v38, v7, v7
	v_mul_f32_e32 v39, v3, v3
	s_nop 0
	v_fma_f32 v36, v6, v6, v38
	v_fma_f32 v37, v2, v2, v39
	v_fma_f32 v36, v8, v8, v36
	v_fma_f32 v37, v4, v4, v37
	v_fma_f32 v36, v9, v9, v36
	v_fma_f32 v37, v5, v5, v37
	global_load_dwordx4 v[38:41], v[32:33], off
	v_add_f32_e32 v23, v23, v36
	v_add_f32_e32 v23, v23, v37
	ds_bpermute_b32 v1, v1, v23
	s_nop 2
	s_waitcnt lgkmcnt(0)
	v_add_f32_e32 v1, v23, v1
	ds_bpermute_b32 v23, v42, v1
	s_nop 2
	s_waitcnt lgkmcnt(0)
	v_add_f32_e32 v1, v1, v23
	ds_bpermute_b32 v23, v43, v1
	s_nop 2
	s_waitcnt lgkmcnt(0)
	v_add_f32_e32 v1, v1, v23
	ds_bpermute_b32 v23, v44, v1
	s_nop 2
	s_waitcnt lgkmcnt(0)
	v_add_f32_e32 v1, v1, v23
	ds_bpermute_b32 v23, v45, v1
	s_nop 2
	s_waitcnt lgkmcnt(0)
	v_add_f32_e32 v1, v1, v23
	ds_bpermute_b32 v23, v46, v1
	s_waitcnt lgkmcnt(0)
	v_add_f32_e32 v1, v1, v23
	v_fmamk_f32 v1, v1, 0x3a800000, v188
	v_cmp_gt_f32_e32 vcc, s0, v1
	v_readlane_b32 s0, v245, 5
	v_readlane_b32 s1, v245, 6
	v_mul_f32_e32 v23, 0x4b800000, v1
	v_cndmask_b32_e32 v1, v1, v23, vcc
	v_lshl_add_u64 v[42:43], v[18:19], 2, s[0:1]
	s_mov_b64 s[0:1], 0x1000
	v_lshl_add_u64 v[18:19], v[42:43], 0, s[0:1]
	v_readlane_b32 s0, v247, 56
	v_readlane_b32 s1, v247, 57
	v_rsq_f32_e32 v1, v1
	s_nop 0
	v_lshl_add_u64 v[36:37], s[0:1], 0, v[34:35]
	v_lshl_add_u64 v[34:35], v[42:43], 0, v[20:21]
	v_lshl_add_u64 v[20:21], v[18:19], 0, v[20:21]
	global_load_dwordx4 v[46:49], v[20:21], off
	global_load_dwordx4 v[42:45], v[34:35], off
	v_mul_f32_e32 v23, 0x45800000, v1
	v_cndmask_b32_e32 v24, v1, v23, vcc
	v_pk_mul_f32 v[14:15], v[14:15], v[24:25] op_sel_hi:[1,0]
	v_mov_b32_e32 v23, v0
	v_pk_mul_f32 v[10:11], v[10:11], v[24:25] op_sel_hi:[1,0]
	v_pk_mul_f32 v[12:13], v[12:13], v[24:25] op_sel_hi:[1,0]
	v_pk_mul_f32 v[6:7], v[6:7], v[24:25] op_sel_hi:[1,0]
	v_pk_mul_f32 v[8:9], v[8:9], v[24:25] op_sel_hi:[1,0]
	v_pk_mul_f32 v[2:3], v[2:3], v[24:25] op_sel_hi:[1,0]
	v_pk_mul_f32 v[4:5], v[4:5], v[24:25] op_sel_hi:[1,0]
	s_mov_b64 s[0:1], 0
	s_waitcnt vmcnt(2)
	v_pk_mul_f32 v[14:15], v[38:39], v[14:15]
	s_waitcnt vmcnt(1)
	v_pk_add_f32 v[20:21], v[46:47], 1.0 op_sel_hi:[1,0]
	s_waitcnt vmcnt(0)
	v_pk_fma_f32 v[14:15], v[20:21], v[14:15], v[42:43]
	s_nop 0
	v_cvt_pk_bf16_f32 v20, v14, v15
	v_pk_mul_f32 v[14:15], v[16:17], v[24:25] op_sel_hi:[1,0]
	v_pk_add_f32 v[16:17], v[48:49], 1.0 op_sel_hi:[1,0]
	v_pk_mul_f32 v[14:15], v[40:41], v[14:15]
	s_nop 0
	v_pk_fma_f32 v[14:15], v[16:17], v[14:15], v[44:45]
	v_lshl_add_u64 v[16:17], v[18:19], 0, v[26:27]
	v_cvt_pk_bf16_f32 v21, v14, v15
	v_lshl_add_u64 v[14:15], v[36:37], 0, v[22:23]
	global_store_dwordx2 v[14:15], v[20:21], off
	global_load_dwordx4 v[20:23], v[32:33], off offset:1024
	s_nop 0
	global_load_dwordx4 v[36:39], v[34:35], off offset:1024
	global_load_dwordx4 v[40:43], v[16:17], off
	s_waitcnt vmcnt(2)
	v_pk_mul_f32 v[10:11], v[20:21], v[10:11]
	v_pk_mul_f32 v[12:13], v[22:23], v[12:13]
	s_waitcnt vmcnt(0)
	v_pk_add_f32 v[16:17], v[40:41], 1.0 op_sel_hi:[1,0]
	s_nop 0
	v_pk_fma_f32 v[10:11], v[16:17], v[10:11], v[36:37]
	v_pk_add_f32 v[16:17], v[42:43], 1.0 op_sel_hi:[1,0]
	v_cvt_pk_bf16_f32 v10, v10, v11
	v_pk_fma_f32 v[12:13], v[16:17], v[12:13], v[38:39]
	v_lshl_add_u64 v[16:17], v[18:19], 0, v[28:29]
	v_cvt_pk_bf16_f32 v11, v12, v13
	global_store_dwordx2 v[14:15], v[10:11], off offset:512
	global_load_dwordx4 v[10:13], v[32:33], off offset:2048
	s_nop 0
	global_load_dwordx4 v[20:23], v[34:35], off offset:2048
	global_load_dwordx4 v[26:29], v[16:17], off
	v_lshl_add_u64 v[16:17], v[18:19], 0, v[30:31]
	s_waitcnt vmcnt(2)
	v_pk_mul_f32 v[6:7], v[10:11], v[6:7]
	v_pk_mul_f32 v[8:9], v[12:13], v[8:9]
	s_waitcnt vmcnt(0)
	v_pk_add_f32 v[10:11], v[26:27], 1.0 op_sel_hi:[1,0]
	s_nop 0
	v_pk_fma_f32 v[6:7], v[10:11], v[6:7], v[20:21]
	v_pk_add_f32 v[10:11], v[28:29], 1.0 op_sel_hi:[1,0]
	v_cvt_pk_bf16_f32 v6, v6, v7
	v_pk_fma_f32 v[8:9], v[10:11], v[8:9], v[22:23]
	s_nop 0
	v_cvt_pk_bf16_f32 v7, v8, v9
	global_store_dwordx2 v[14:15], v[6:7], off offset:1024
	global_load_dwordx4 v[6:9], v[32:33], off offset:3072
	s_nop 0
	global_load_dwordx4 v[10:13], v[34:35], off offset:3072
	s_waitcnt vmcnt(1)
	v_pk_mul_f32 v[2:3], v[6:7], v[2:3]
	global_load_dwordx4 v[16:19], v[16:17], off
	v_pk_mul_f32 v[4:5], v[8:9], v[4:5]
	s_waitcnt vmcnt(0)
	v_pk_add_f32 v[6:7], v[16:17], 1.0 op_sel_hi:[1,0]
	s_nop 0
	v_pk_fma_f32 v[2:3], v[2:3], v[6:7], v[10:11]
	v_pk_add_f32 v[6:7], v[18:19], 1.0 op_sel_hi:[1,0]
	v_cvt_pk_bf16_f32 v2, v2, v3
	v_pk_fma_f32 v[4:5], v[4:5], v[6:7], v[12:13]
	s_nop 0
	v_cvt_pk_bf16_f32 v3, v4, v5
	global_store_dwordx2 v[14:15], v[2:3], off offset:1536
